# v066 plus touch-prefetch of the remaining residual rows at the start of the FFN-out residual-LayerNorm epilogue (de-serialise batched loads)
# baseline (speedup 1.0000x reference)
.LBB0_1847:
	s_lshl_b32 s11, s59, 8
	v_mov_b32_e32 v252, v243
	s_add_i32 s12, s11, s48
	s_lshl_b32 s13, s10, 8
	v_mov_b32_e32 v0, v251
	s_or_b32 s13, s13, s49
	v_add_u32_e32 v234, s12, v252
	v_ashrrev_i32_e32 v235, 31, v234
	v_lshl_add_u32 v232, v0, 3, s13
	v_add_u32_e32 v138, 16, v234
	v_ashrrev_i32_e32 v233, 31, v232
	v_lshlrev_b64 v[130:131], 12, v[234:235]
	v_ashrrev_i32_e32 v139, 31, v138
	v_lshl_add_u64 v[130:131], s[70:71], 0, v[130:131]
	v_lshlrev_b64 v[238:239], 1, v[232:233]
	v_lshlrev_b64 v[138:139], 12, v[138:139]
	v_lshl_add_u64 v[134:135], v[130:131], 0, v[238:239]
	v_mov_b32_e32 v207, 0
	v_mov_b32_e32 v206, 0x20000
	v_lshl_add_u64 v[194:195], v[134:135], 0, v[206:207]
	v_mov_b32_e32 v206, 0x30000
	v_lshl_add_u64 v[196:197], v[134:135], 0, v[206:207]
	v_mov_b32_e32 v206, 0x80000
	v_lshl_add_u64 v[198:199], v[134:135], 0, v[206:207]
	v_mov_b32_e32 v206, 0x90000
	v_lshl_add_u64 v[200:201], v[134:135], 0, v[206:207]
	v_mov_b32_e32 v206, 0xa0000
	v_lshl_add_u64 v[202:203], v[134:135], 0, v[206:207]
	v_mov_b32_e32 v206, 0xb0000
	v_lshl_add_u64 v[204:205], v[134:135], 0, v[206:207]
	v_lshl_add_u64 v[138:139], s[70:71], 0, v[138:139]
	global_load_dwordx4 v[130:133], v[134:135], off
	s_nop 0
	global_load_dwordx4 v[134:137], v[134:135], off offset:256
	v_lshl_add_u64 v[142:143], v[138:139], 0, v[238:239]
	s_min_i32 s12, s59, 64
	global_load_dwordx4 v[138:141], v[142:143], off
	s_nop 0
	global_load_dwordx4 v[142:145], v[142:143], off offset:256
	global_load_dword v208, v[194:195], off
	global_load_dword v208, v[194:195], off offset:256
	global_load_dword v208, v[196:197], off
	global_load_dword v208, v[196:197], off offset:256
	global_load_dword v208, v[198:199], off
	global_load_dword v208, v[198:199], off offset:256
	global_load_dword v208, v[200:201], off
	global_load_dword v208, v[200:201], off offset:256
	global_load_dword v208, v[202:203], off
	global_load_dword v208, v[202:203], off offset:256
	global_load_dword v208, v[204:205], off
	global_load_dword v208, v[204:205], off offset:256
	s_ashr_i32 s13, s12, 4
	s_mul_hi_i32 s12, s13, 0xc000
	s_mul_i32 s13, s13, 0xc000
	s_add_u32 s14, s87, s13
	s_addc_u32 s15, s89, s12
	v_lshlrev_b64 v[236:237], 2, v[232:233]
	v_lshl_add_u64 v[146:147], s[14:15], 0, v[236:237]
	global_load_dwordx4 v[206:209], v[146:147], off
	global_load_dwordx4 v[202:205], v[146:147], off offset:16
	global_load_dwordx4 v[198:201], v[146:147], off offset:512
	global_load_dwordx4 v[194:197], v[146:147], off offset:528
	s_add_u32 s14, s72, s13
	s_addc_u32 s15, s25, s12
	s_and_b64 vcc, exec, s[0:1]
	s_waitcnt vmcnt(0)
	v_cvt_f32_f16_e32 v148, v130
	v_cvt_f32_f16_sdwa v149, v130 dst_sel:DWORD dst_unused:UNUSED_PAD src0_sel:WORD_1
	v_cvt_f32_f16_e32 v150, v132
	v_cvt_f32_f16_sdwa v151, v132 dst_sel:DWORD dst_unused:UNUSED_PAD src0_sel:WORD_1
	v_cvt_f32_f16_e32 v152, v134
	v_cvt_f32_f16_sdwa v153, v134 dst_sel:DWORD dst_unused:UNUSED_PAD src0_sel:WORD_1
	v_cvt_f32_f16_e32 v158, v140
	v_cvt_f32_f16_sdwa v159, v140 dst_sel:DWORD dst_unused:UNUSED_PAD src0_sel:WORD_1
	v_cvt_f32_f16_e32 v160, v142
	v_cvt_f32_f16_sdwa v161, v142 dst_sel:DWORD dst_unused:UNUSED_PAD src0_sel:WORD_1
	v_cvt_f32_f16_e32 v146, v131
	v_cvt_f32_f16_sdwa v147, v131 dst_sel:DWORD dst_unused:UNUSED_PAD src0_sel:WORD_1
	v_cvt_f32_f16_e32 v130, v133
	v_cvt_f32_f16_sdwa v131, v133 dst_sel:DWORD dst_unused:UNUSED_PAD src0_sel:WORD_1
	v_cvt_f32_f16_e32 v132, v135
	v_cvt_f32_f16_sdwa v133, v135 dst_sel:DWORD dst_unused:UNUSED_PAD src0_sel:WORD_1
	v_cvt_f32_f16_e32 v134, v137
	v_cvt_f32_f16_sdwa v135, v137 dst_sel:DWORD dst_unused:UNUSED_PAD src0_sel:WORD_1
	v_cvt_f32_f16_e32 v154, v136
	v_cvt_f32_f16_sdwa v155, v136 dst_sel:DWORD dst_unused:UNUSED_PAD src0_sel:WORD_1
	v_cvt_f32_f16_e32 v136, v139
	v_cvt_f32_f16_sdwa v137, v139 dst_sel:DWORD dst_unused:UNUSED_PAD src0_sel:WORD_1
	v_cvt_f32_f16_e32 v156, v138
	v_cvt_f32_f16_sdwa v157, v138 dst_sel:DWORD dst_unused:UNUSED_PAD src0_sel:WORD_1
	v_cvt_f32_f16_e32 v138, v141
	v_cvt_f32_f16_sdwa v139, v141 dst_sel:DWORD dst_unused:UNUSED_PAD src0_sel:WORD_1
	v_cvt_f32_f16_e32 v140, v143
	v_cvt_f32_f16_sdwa v141, v143 dst_sel:DWORD dst_unused:UNUSED_PAD src0_sel:WORD_1
	v_cvt_f32_f16_e32 v162, v144
	v_cvt_f32_f16_sdwa v163, v144 dst_sel:DWORD dst_unused:UNUSED_PAD src0_sel:WORD_1
	v_cvt_f32_f16_e32 v142, v145
	v_cvt_f32_f16_sdwa v143, v145 dst_sel:DWORD dst_unused:UNUSED_PAD src0_sel:WORD_1
	v_pk_mul_f32 v[144:145], v[148:149], s[66:67] op_sel_hi:[1,0]
	v_pk_mul_f32 v[148:149], v[150:151], s[66:67] op_sel_hi:[1,0]
	v_pk_mul_f32 v[150:151], v[152:153], s[66:67] op_sel_hi:[1,0]
	v_pk_fma_f32 v[186:187], v[122:123], v[202:203], v[148:149]
	v_pk_fma_f32 v[178:179], v[118:119], v[198:199], v[150:151]
	v_pk_mul_f32 v[118:119], v[158:159], s[66:67] op_sel_hi:[1,0]
	v_pk_mul_f32 v[122:123], v[160:161], s[66:67] op_sel_hi:[1,0]
	v_pk_mul_f32 v[152:153], v[154:155], s[66:67] op_sel_hi:[1,0]
	v_pk_fma_f32 v[170:171], v[106:107], v[202:203], v[118:119]
	v_pk_mul_f32 v[106:107], v[140:141], s[66:67] op_sel_hi:[1,0]
	v_pk_fma_f32 v[154:155], v[102:103], v[198:199], v[122:123]
	v_pk_mul_f32 v[102:103], v[162:163], s[66:67] op_sel_hi:[1,0]
	v_pk_fma_f32 v[182:183], v[110:111], v[194:195], v[152:153]
	v_pk_mul_f32 v[110:111], v[156:157], s[66:67] op_sel_hi:[1,0]
	v_pk_fma_f32 v[156:157], v[104:105], v[200:201], v[106:107]
	v_pk_fma_f32 v[158:159], v[98:99], v[194:195], v[102:103]
	v_add_u32_e32 v98, 32, v234
	v_add_u32_e32 v106, 48, v234
	v_pk_mul_f32 v[132:133], v[132:133], s[66:67] op_sel_hi:[1,0]
	v_pk_mul_f32 v[134:135], v[134:135], s[66:67] op_sel_hi:[1,0]
	v_ashrrev_i32_e32 v99, 31, v98
	v_ashrrev_i32_e32 v107, 31, v106
	v_pk_mul_f32 v[146:147], v[146:147], s[66:67] op_sel_hi:[1,0]
	v_pk_mul_f32 v[130:131], v[130:131], s[66:67] op_sel_hi:[1,0]
	v_pk_fma_f32 v[180:181], v[120:121], v[200:201], v[132:133]
	v_pk_fma_f32 v[184:185], v[112:113], v[196:197], v[134:135]
	v_pk_mul_f32 v[112:113], v[136:137], s[66:67] op_sel_hi:[1,0]
	v_pk_mul_f32 v[120:121], v[138:139], s[66:67] op_sel_hi:[1,0]
	v_pk_mul_f32 v[104:105], v[142:143], s[66:67] op_sel_hi:[1,0]
	v_lshlrev_b64 v[98:99], 12, v[98:99]
	v_lshlrev_b64 v[106:107], 12, v[106:107]
	v_pk_fma_f32 v[192:193], v[128:129], v[208:209], v[146:147]
	v_pk_fma_f32 v[190:191], v[126:127], v[206:207], v[144:145]
	v_pk_fma_f32 v[188:189], v[124:125], v[204:205], v[130:131]
	v_pk_fma_f32 v[176:177], v[116:117], v[208:209], v[112:113]
	v_pk_fma_f32 v[174:175], v[114:115], v[206:207], v[110:111]
	v_pk_fma_f32 v[172:173], v[108:109], v[204:205], v[120:121]
	v_pk_fma_f32 v[160:161], v[100:101], v[196:197], v[104:105]
	v_lshl_add_u64 v[98:99], s[70:71], 0, v[98:99]
	v_lshl_add_u64 v[106:107], s[70:71], 0, v[106:107]
	v_lshl_add_u64 v[102:103], v[98:99], 0, v[238:239]
	v_lshl_add_u64 v[110:111], v[106:107], 0, v[238:239]
	global_load_dwordx4 v[98:101], v[102:103], off
	s_nop 0
	global_load_dwordx4 v[102:105], v[102:103], off offset:256
	s_nop 0
	global_load_dwordx4 v[106:109], v[110:111], off
	s_nop 0
	global_load_dwordx4 v[110:113], v[110:111], off offset:256
	s_waitcnt vmcnt(3)
	v_cvt_f32_f16_e32 v116, v98
	v_cvt_f32_f16_sdwa v117, v98 dst_sel:DWORD dst_unused:UNUSED_PAD src0_sel:WORD_1
	v_cvt_f32_f16_e32 v118, v100
	v_cvt_f32_f16_sdwa v119, v100 dst_sel:DWORD dst_unused:UNUSED_PAD src0_sel:WORD_1
	s_waitcnt vmcnt(2)
	v_cvt_f32_f16_e32 v120, v102
	v_cvt_f32_f16_sdwa v121, v102 dst_sel:DWORD dst_unused:UNUSED_PAD src0_sel:WORD_1
	v_cvt_f32_f16_e32 v122, v104
	v_cvt_f32_f16_sdwa v123, v104 dst_sel:DWORD dst_unused:UNUSED_PAD src0_sel:WORD_1
	s_waitcnt vmcnt(1)
	v_cvt_f32_f16_e32 v124, v106
	v_cvt_f32_f16_sdwa v125, v106 dst_sel:DWORD dst_unused:UNUSED_PAD src0_sel:WORD_1
	v_cvt_f32_f16_e32 v126, v108
	v_cvt_f32_f16_sdwa v127, v108 dst_sel:DWORD dst_unused:UNUSED_PAD src0_sel:WORD_1
	s_waitcnt vmcnt(0)
	v_cvt_f32_f16_e32 v128, v110
	v_cvt_f32_f16_sdwa v129, v110 dst_sel:DWORD dst_unused:UNUSED_PAD src0_sel:WORD_1
	v_cvt_f32_f16_e32 v130, v112
	v_cvt_f32_f16_sdwa v131, v112 dst_sel:DWORD dst_unused:UNUSED_PAD src0_sel:WORD_1
	v_cvt_f32_f16_e32 v114, v99
	v_cvt_f32_f16_sdwa v115, v99 dst_sel:DWORD dst_unused:UNUSED_PAD src0_sel:WORD_1
	v_cvt_f32_f16_e32 v98, v101
	v_cvt_f32_f16_sdwa v99, v101 dst_sel:DWORD dst_unused:UNUSED_PAD src0_sel:WORD_1
	v_cvt_f32_f16_e32 v100, v103
	v_cvt_f32_f16_sdwa v101, v103 dst_sel:DWORD dst_unused:UNUSED_PAD src0_sel:WORD_1
	v_cvt_f32_f16_e32 v102, v105
	v_cvt_f32_f16_sdwa v103, v105 dst_sel:DWORD dst_unused:UNUSED_PAD src0_sel:WORD_1
	v_cvt_f32_f16_e32 v104, v107
	v_cvt_f32_f16_sdwa v105, v107 dst_sel:DWORD dst_unused:UNUSED_PAD src0_sel:WORD_1
	v_cvt_f32_f16_e32 v106, v109
	v_cvt_f32_f16_sdwa v107, v109 dst_sel:DWORD dst_unused:UNUSED_PAD src0_sel:WORD_1
	v_cvt_f32_f16_e32 v108, v111
	v_cvt_f32_f16_sdwa v109, v111 dst_sel:DWORD dst_unused:UNUSED_PAD src0_sel:WORD_1
	v_cvt_f32_f16_e32 v110, v113
	v_cvt_f32_f16_sdwa v111, v113 dst_sel:DWORD dst_unused:UNUSED_PAD src0_sel:WORD_1
	v_pk_mul_f32 v[112:113], v[116:117], s[66:67] op_sel_hi:[1,0]
	v_pk_mul_f32 v[116:117], v[118:119], s[66:67] op_sel_hi:[1,0]
	v_pk_mul_f32 v[118:119], v[120:121], s[66:67] op_sel_hi:[1,0]
	v_pk_mul_f32 v[120:121], v[122:123], s[66:67] op_sel_hi:[1,0]
	v_pk_mul_f32 v[122:123], v[124:125], s[66:67] op_sel_hi:[1,0]
	v_pk_mul_f32 v[124:125], v[126:127], s[66:67] op_sel_hi:[1,0]
	v_pk_mul_f32 v[126:127], v[128:129], s[66:67] op_sel_hi:[1,0]
	v_pk_mul_f32 v[128:129], v[130:131], s[66:67] op_sel_hi:[1,0]
	v_pk_fma_f32 v[150:151], v[78:79], v[198:199], v[118:119]
	v_pk_fma_f32 v[118:119], v[66:67], v[194:195], v[128:129]
	v_add_u32_e32 v66, 0x80, v234
	v_ashrrev_i32_e32 v67, 31, v66
	v_pk_mul_f32 v[114:115], v[114:115], s[66:67] op_sel_hi:[1,0]
	v_pk_mul_f32 v[98:99], v[98:99], s[66:67] op_sel_hi:[1,0]
	v_pk_mul_f32 v[100:101], v[100:101], s[66:67] op_sel_hi:[1,0]
	v_pk_mul_f32 v[102:103], v[102:103], s[66:67] op_sel_hi:[1,0]
	v_pk_mul_f32 v[104:105], v[104:105], s[66:67] op_sel_hi:[1,0]
	v_pk_mul_f32 v[106:107], v[106:107], s[66:67] op_sel_hi:[1,0]
	v_pk_mul_f32 v[108:109], v[108:109], s[66:67] op_sel_hi:[1,0]
	v_pk_mul_f32 v[110:111], v[110:111], s[66:67] op_sel_hi:[1,0]
	v_lshlrev_b64 v[66:67], 12, v[66:67]
	v_pk_fma_f32 v[168:169], v[96:97], v[208:209], v[114:115]
	v_pk_fma_f32 v[166:167], v[94:95], v[206:207], v[112:113]
	v_pk_fma_f32 v[164:165], v[92:93], v[204:205], v[98:99]
	v_pk_fma_f32 v[162:163], v[90:91], v[202:203], v[116:117]
	v_pk_fma_f32 v[152:153], v[80:81], v[200:201], v[100:101]
	v_pk_fma_f32 v[148:149], v[76:77], v[196:197], v[102:103]
	v_pk_fma_f32 v[146:147], v[74:75], v[194:195], v[120:121]
	v_pk_fma_f32 v[136:137], v[88:89], v[208:209], v[104:105]
	v_pk_fma_f32 v[134:135], v[86:87], v[206:207], v[122:123]
	v_pk_fma_f32 v[132:133], v[84:85], v[204:205], v[106:107]
	v_pk_fma_f32 v[130:131], v[82:83], v[202:203], v[124:125]
	v_pk_fma_f32 v[116:117], v[72:73], v[200:201], v[108:109]
	v_pk_fma_f32 v[114:115], v[70:71], v[198:199], v[126:127]
	v_pk_fma_f32 v[120:121], v[68:69], v[196:197], v[110:111]
	v_lshl_add_u64 v[66:67], s[70:71], 0, v[66:67]
	v_add_u32_e32 v74, 0x90, v234
	v_lshl_add_u64 v[70:71], v[66:67], 0, v[238:239]
	v_ashrrev_i32_e32 v75, 31, v74
	global_load_dwordx4 v[66:69], v[70:71], off
	s_nop 0
	global_load_dwordx4 v[70:73], v[70:71], off offset:256
	v_lshlrev_b64 v[74:75], 12, v[74:75]
	v_lshl_add_u64 v[74:75], s[70:71], 0, v[74:75]
	v_lshl_add_u64 v[78:79], v[74:75], 0, v[238:239]
	global_load_dwordx4 v[74:77], v[78:79], off
	s_nop 0
	global_load_dwordx4 v[78:81], v[78:79], off offset:256
	v_add_u32_e32 v82, 0xa0, v234
	v_ashrrev_i32_e32 v83, 31, v82
	v_lshlrev_b64 v[82:83], 12, v[82:83]
	s_waitcnt vmcnt(3)
	v_cvt_f32_f16_e32 v86, v66
	v_cvt_f32_f16_sdwa v87, v66 dst_sel:DWORD dst_unused:UNUSED_PAD src0_sel:WORD_1
	v_cvt_f32_f16_e32 v88, v68
	v_cvt_f32_f16_sdwa v89, v68 dst_sel:DWORD dst_unused:UNUSED_PAD src0_sel:WORD_1
	s_waitcnt vmcnt(2)
	v_cvt_f32_f16_e32 v90, v70
	v_cvt_f32_f16_sdwa v91, v70 dst_sel:DWORD dst_unused:UNUSED_PAD src0_sel:WORD_1
	v_cvt_f32_f16_e32 v92, v72
	v_cvt_f32_f16_sdwa v93, v72 dst_sel:DWORD dst_unused:UNUSED_PAD src0_sel:WORD_1
	v_cvt_f32_f16_e32 v84, v67
	v_cvt_f32_f16_sdwa v85, v67 dst_sel:DWORD dst_unused:UNUSED_PAD src0_sel:WORD_1
	v_cvt_f32_f16_e32 v66, v69
	v_cvt_f32_f16_sdwa v67, v69 dst_sel:DWORD dst_unused:UNUSED_PAD src0_sel:WORD_1
	v_cvt_f32_f16_e32 v68, v71
	v_cvt_f32_f16_sdwa v69, v71 dst_sel:DWORD dst_unused:UNUSED_PAD src0_sel:WORD_1
	v_cvt_f32_f16_e32 v70, v73
	v_cvt_f32_f16_sdwa v71, v73 dst_sel:DWORD dst_unused:UNUSED_PAD src0_sel:WORD_1
	s_waitcnt vmcnt(1)
	v_cvt_f32_f16_e32 v72, v75
	v_cvt_f32_f16_sdwa v73, v75 dst_sel:DWORD dst_unused:UNUSED_PAD src0_sel:WORD_1
	v_cvt_f32_f16_e32 v94, v74
	v_cvt_f32_f16_sdwa v95, v74 dst_sel:DWORD dst_unused:UNUSED_PAD src0_sel:WORD_1
	v_cvt_f32_f16_e32 v74, v77
	v_cvt_f32_f16_sdwa v75, v77 dst_sel:DWORD dst_unused:UNUSED_PAD src0_sel:WORD_1
	v_cvt_f32_f16_e32 v96, v76
	v_cvt_f32_f16_sdwa v97, v76 dst_sel:DWORD dst_unused:UNUSED_PAD src0_sel:WORD_1
	s_waitcnt vmcnt(0)
	v_cvt_f32_f16_e32 v76, v79
	v_cvt_f32_f16_sdwa v77, v79 dst_sel:DWORD dst_unused:UNUSED_PAD src0_sel:WORD_1
	v_cvt_f32_f16_e32 v98, v78
	v_cvt_f32_f16_sdwa v99, v78 dst_sel:DWORD dst_unused:UNUSED_PAD src0_sel:WORD_1
	v_cvt_f32_f16_e32 v78, v81
	v_cvt_f32_f16_sdwa v79, v81 dst_sel:DWORD dst_unused:UNUSED_PAD src0_sel:WORD_1
	v_cvt_f32_f16_e32 v100, v80
	v_cvt_f32_f16_sdwa v101, v80 dst_sel:DWORD dst_unused:UNUSED_PAD src0_sel:WORD_1
	v_pk_mul_f32 v[80:81], v[86:87], s[66:67] op_sel_hi:[1,0]
	v_pk_mul_f32 v[86:87], v[88:89], s[66:67] op_sel_hi:[1,0]
	v_pk_mul_f32 v[88:89], v[90:91], s[66:67] op_sel_hi:[1,0]
	v_pk_mul_f32 v[90:91], v[92:93], s[66:67] op_sel_hi:[1,0]
	v_pk_mul_f32 v[84:85], v[84:85], s[66:67] op_sel_hi:[1,0]
	v_pk_fma_f32 v[122:123], v[42:43], v[194:195], v[90:91]
	v_add_u32_e32 v42, 0xb0, v234
	v_ashrrev_i32_e32 v43, 31, v42
	v_pk_mul_f32 v[66:67], v[66:67], s[66:67] op_sel_hi:[1,0]
	v_pk_mul_f32 v[68:69], v[68:69], s[66:67] op_sel_hi:[1,0]
	v_pk_mul_f32 v[70:71], v[70:71], s[66:67] op_sel_hi:[1,0]
	v_pk_mul_f32 v[92:93], v[94:95], s[66:67] op_sel_hi:[1,0]
	v_pk_mul_f32 v[72:73], v[72:73], s[66:67] op_sel_hi:[1,0]
	v_pk_mul_f32 v[94:95], v[96:97], s[66:67] op_sel_hi:[1,0]
	v_pk_mul_f32 v[74:75], v[74:75], s[66:67] op_sel_hi:[1,0]
	v_pk_mul_f32 v[98:99], v[98:99], s[66:67] op_sel_hi:[1,0]
	v_pk_mul_f32 v[76:77], v[76:77], s[66:67] op_sel_hi:[1,0]
	v_pk_mul_f32 v[100:101], v[100:101], s[66:67] op_sel_hi:[1,0]
	v_pk_mul_f32 v[78:79], v[78:79], s[66:67] op_sel_hi:[1,0]
	v_lshlrev_b64 v[42:43], 12, v[42:43]
	v_pk_fma_f32 v[144:145], v[64:65], v[208:209], v[84:85]
	v_pk_fma_f32 v[142:143], v[62:63], v[206:207], v[80:81]
	v_pk_fma_f32 v[140:141], v[60:61], v[204:205], v[66:67]
	v_pk_fma_f32 v[138:139], v[58:59], v[202:203], v[86:87]
	v_pk_fma_f32 v[128:129], v[48:49], v[200:201], v[68:69]
	v_pk_fma_f32 v[126:127], v[46:47], v[198:199], v[88:89]
	v_pk_fma_f32 v[124:125], v[44:45], v[196:197], v[70:71]
	v_pk_fma_f32 v[112:113], v[56:57], v[208:209], v[72:73]
	v_pk_fma_f32 v[110:111], v[54:55], v[206:207], v[92:93]
	v_pk_fma_f32 v[108:109], v[52:53], v[204:205], v[74:75]
	v_pk_fma_f32 v[106:107], v[50:51], v[202:203], v[94:95]
	v_pk_fma_f32 v[96:97], v[40:41], v[200:201], v[76:77]
	v_pk_fma_f32 v[94:95], v[38:39], v[198:199], v[98:99]
	v_pk_fma_f32 v[92:93], v[36:37], v[196:197], v[78:79]
	v_pk_fma_f32 v[90:91], v[34:35], v[194:195], v[100:101]
	v_lshl_add_u64 v[34:35], s[70:71], 0, v[82:83]
	v_lshl_add_u64 v[42:43], s[70:71], 0, v[42:43]
	v_lshl_add_u64 v[38:39], v[34:35], 0, v[238:239]
	v_lshl_add_u64 v[42:43], v[42:43], 0, v[238:239]
	global_load_dwordx4 v[34:37], v[38:39], off
	s_nop 0
	global_load_dwordx4 v[38:41], v[38:39], off offset:256
	s_nop 0
	global_load_dwordx4 v[44:47], v[42:43], off
	global_load_dwordx4 v[48:51], v[42:43], off offset:256
	v_lshl_add_u64 v[42:43], s[94:95], 0, v[236:237]
	s_waitcnt vmcnt(3)
	v_cvt_f32_f16_e32 v52, v35
	v_cvt_f32_f16_sdwa v53, v35 dst_sel:DWORD dst_unused:UNUSED_PAD src0_sel:WORD_1
	v_cvt_f32_f16_e32 v54, v34
	v_cvt_f32_f16_sdwa v55, v34 dst_sel:DWORD dst_unused:UNUSED_PAD src0_sel:WORD_1
	v_cvt_f32_f16_e32 v34, v37
	v_cvt_f32_f16_sdwa v35, v37 dst_sel:DWORD dst_unused:UNUSED_PAD src0_sel:WORD_1
	v_cvt_f32_f16_e32 v56, v36
	v_cvt_f32_f16_sdwa v57, v36 dst_sel:DWORD dst_unused:UNUSED_PAD src0_sel:WORD_1
	s_waitcnt vmcnt(2)
	v_cvt_f32_f16_e32 v36, v39
	v_cvt_f32_f16_sdwa v37, v39 dst_sel:DWORD dst_unused:UNUSED_PAD src0_sel:WORD_1
	v_cvt_f32_f16_e32 v58, v38
	v_cvt_f32_f16_sdwa v59, v38 dst_sel:DWORD dst_unused:UNUSED_PAD src0_sel:WORD_1
	v_cvt_f32_f16_e32 v38, v41
	v_cvt_f32_f16_sdwa v39, v41 dst_sel:DWORD dst_unused:UNUSED_PAD src0_sel:WORD_1
	v_cvt_f32_f16_e32 v60, v40
	v_cvt_f32_f16_sdwa v61, v40 dst_sel:DWORD dst_unused:UNUSED_PAD src0_sel:WORD_1
	s_waitcnt vmcnt(1)
	v_cvt_f32_f16_e32 v40, v45
	v_cvt_f32_f16_sdwa v41, v45 dst_sel:DWORD dst_unused:UNUSED_PAD src0_sel:WORD_1
	v_cvt_f32_f16_e32 v62, v44
	v_cvt_f32_f16_sdwa v63, v44 dst_sel:DWORD dst_unused:UNUSED_PAD src0_sel:WORD_1
	v_cvt_f32_f16_e32 v44, v47
	v_cvt_f32_f16_sdwa v45, v47 dst_sel:DWORD dst_unused:UNUSED_PAD src0_sel:WORD_1
	v_cvt_f32_f16_e32 v64, v46
	v_cvt_f32_f16_sdwa v65, v46 dst_sel:DWORD dst_unused:UNUSED_PAD src0_sel:WORD_1
	s_waitcnt vmcnt(0)
	v_cvt_f32_f16_e32 v46, v49
	v_cvt_f32_f16_sdwa v47, v49 dst_sel:DWORD dst_unused:UNUSED_PAD src0_sel:WORD_1
	v_cvt_f32_f16_e32 v66, v48
	v_cvt_f32_f16_sdwa v67, v48 dst_sel:DWORD dst_unused:UNUSED_PAD src0_sel:WORD_1
	v_cvt_f32_f16_e32 v48, v51
	v_cvt_f32_f16_sdwa v49, v51 dst_sel:DWORD dst_unused:UNUSED_PAD src0_sel:WORD_1
	v_cvt_f32_f16_e32 v68, v50
	v_cvt_f32_f16_sdwa v69, v50 dst_sel:DWORD dst_unused:UNUSED_PAD src0_sel:WORD_1
	v_pk_mul_f32 v[50:51], v[54:55], s[66:67] op_sel_hi:[1,0]
	v_pk_mul_f32 v[52:53], v[52:53], s[66:67] op_sel_hi:[1,0]
	v_pk_mul_f32 v[54:55], v[56:57], s[66:67] op_sel_hi:[1,0]
	v_pk_mul_f32 v[34:35], v[34:35], s[66:67] op_sel_hi:[1,0]
	v_pk_mul_f32 v[56:57], v[58:59], s[66:67] op_sel_hi:[1,0]
	v_pk_mul_f32 v[36:37], v[36:37], s[66:67] op_sel_hi:[1,0]
	v_pk_mul_f32 v[58:59], v[60:61], s[66:67] op_sel_hi:[1,0]
	v_pk_mul_f32 v[38:39], v[38:39], s[66:67] op_sel_hi:[1,0]
	v_pk_mul_f32 v[60:61], v[62:63], s[66:67] op_sel_hi:[1,0]
	v_pk_mul_f32 v[40:41], v[40:41], s[66:67] op_sel_hi:[1,0]
	v_pk_mul_f32 v[70:71], v[64:65], s[66:67] op_sel_hi:[1,0]
	v_pk_mul_f32 v[44:45], v[44:45], s[66:67] op_sel_hi:[1,0]
	v_pk_mul_f32 v[66:67], v[66:67], s[66:67] op_sel_hi:[1,0]
	v_pk_mul_f32 v[46:47], v[46:47], s[66:67] op_sel_hi:[1,0]
	v_pk_mul_f32 v[68:69], v[68:69], s[66:67] op_sel_hi:[1,0]
	v_pk_mul_f32 v[48:49], v[48:49], s[66:67] op_sel_hi:[1,0]
	v_pk_fma_f32 v[104:105], v[32:33], v[208:209], v[52:53]
	v_pk_fma_f32 v[102:103], v[30:31], v[206:207], v[50:51]
	v_pk_fma_f32 v[100:101], v[28:29], v[204:205], v[34:35]
	v_pk_fma_f32 v[98:99], v[26:27], v[202:203], v[54:55]
	v_pk_fma_f32 v[88:89], v[16:17], v[200:201], v[36:37]
	v_pk_fma_f32 v[86:87], v[14:15], v[198:199], v[56:57]
	v_pk_fma_f32 v[84:85], v[12:13], v[196:197], v[38:39]
	v_pk_fma_f32 v[82:83], v[10:11], v[194:195], v[58:59]
	v_pk_fma_f32 v[64:65], v[24:25], v[208:209], v[40:41]
	v_pk_fma_f32 v[62:63], v[22:23], v[206:207], v[60:61]
	v_pk_fma_f32 v[60:61], v[20:21], v[204:205], v[44:45]
	v_pk_fma_f32 v[58:59], v[18:19], v[202:203], v[70:71]
	v_pk_fma_f32 v[16:17], v[8:9], v[200:201], v[46:47]
	v_pk_fma_f32 v[14:15], v[6:7], v[198:199], v[66:67]
	v_pk_fma_f32 v[12:13], v[4:5], v[196:197], v[48:49]
	v_pk_fma_f32 v[10:11], v[2:3], v[194:195], v[68:69]
	v_lshl_add_u64 v[18:19], s[20:21], 0, v[236:237]
	global_load_dwordx4 v[66:69], v[42:43], off
	global_load_dwordx4 v[70:73], v[18:19], off
	v_lshl_add_u64 v[194:195], v[232:233], 2, s[14:15]
	s_waitcnt vmcnt(1)
	v_mov_b64_e32 v[38:39], v[66:67]
	v_mov_b64_e32 v[34:35], v[66:67]
	v_mov_b64_e32 v[40:41], v[68:69]
	v_mov_b64_e32 v[36:37], v[68:69]
	s_cbranch_vccz .LBB0_1849
	v_add_co_u32_e32 v2, vcc, 0x2000, v194
	s_nop 1
	v_addc_co_u32_e32 v3, vcc, 0, v195, vcc
	global_load_dwordx4 v[38:41], v[2:3], off
	global_load_dwordx4 v[34:37], v[194:195], off
